# W1 epilogue stores with nt (streaming) so U does not evict the residual stream from the Infinity Cache
# speedup vs baseline: 1.0110x; 1.0016x over previous
.LBB0_238:
	v_lshl_add_u32 v140, s42, 8, v144
	v_lshl_or_b32 v138, s79, 8, v146
	v_ashrrev_i32_e32 v141, 31, v140
	v_ashrrev_i32_e32 v139, 31, v138
	v_lshlrev_b64 v[142:143], 13, v[140:141]
	v_max_f32_e32 v124, v124, v124
	v_max_f32_e32 v125, v125, v125
	v_max_f32_e32 v126, v126, v126
	v_max_f32_e32 v127, v127, v127
	v_max_f32_e32 v116, v116, v116
	v_max_f32_e32 v117, v117, v117
	v_max_f32_e32 v118, v118, v118
	v_max_f32_e32 v119, v119, v119
	v_max_f32_e32 v112, v112, v112
	v_max_f32_e32 v113, v113, v113
	v_lshl_add_u64 v[164:165], s[2:3], 0, v[142:143]
	v_lshlrev_b64 v[142:143], 1, v[138:139]
	v_max_f32_e32 v124, 0, v124
	v_max_f32_e32 v125, 0, v125
	v_max_f32_e32 v126, 0, v126
	v_max_f32_e32 v127, 0, v127
	v_max_f32_e32 v120, v120, v120
	v_max_f32_e32 v121, v121, v121
	v_max_f32_e32 v122, v122, v122
	v_max_f32_e32 v123, v123, v123
	v_max_f32_e32 v116, 0, v116
	v_max_f32_e32 v117, 0, v117
	v_max_f32_e32 v118, 0, v118
	v_max_f32_e32 v119, 0, v119
	v_max_f32_e32 v112, 0, v112
	v_max_f32_e32 v113, 0, v113
	v_lshl_add_u64 v[138:139], v[164:165], 0, v[142:143]
	v_pk_mul_f32 v[126:127], v[126:127], v[126:127]
	v_pk_mul_f32 v[124:125], v[124:125], v[124:125]
	v_max_f32_e32 v120, 0, v120
	v_max_f32_e32 v121, 0, v121
	v_max_f32_e32 v122, 0, v122
	v_max_f32_e32 v123, 0, v123
	v_pk_mul_f32 v[118:119], v[118:119], v[118:119]
	v_pk_mul_f32 v[116:117], v[116:117], v[116:117]
	v_pk_mul_f32 v[112:113], v[112:113], v[112:113]
	v_cvt_pk_bf16_f32 v124, v124, v125
	v_cvt_pk_bf16_f32 v125, v126, v127
	v_pk_mul_f32 v[122:123], v[122:123], v[122:123]
	v_pk_mul_f32 v[120:121], v[120:121], v[120:121]
	v_max_f32_e32 v108, v108, v108
	v_cvt_pk_bf16_f32 v126, v120, v121
	v_cvt_pk_bf16_f32 v127, v122, v123
	global_store_dwordx4 v[138:139], v[124:127], off nt
	v_cvt_pk_bf16_f32 v116, v116, v117
	v_cvt_pk_bf16_f32 v117, v118, v119
	v_cvt_pk_bf16_f32 v118, v112, v113
	v_or_b32_e32 v112, 16, v140
	v_ashrrev_i32_e32 v113, 31, v112
	v_lshlrev_b64 v[112:113], 13, v[112:113]
	v_max_f32_e32 v109, v109, v109
	v_max_f32_e32 v110, v110, v110
	v_max_f32_e32 v111, v111, v111
	v_max_f32_e32 v100, v100, v100
	v_max_f32_e32 v101, v101, v101
	v_max_f32_e32 v102, v102, v102
	v_max_f32_e32 v103, v103, v103
	v_max_f32_e32 v96, v96, v96
	v_max_f32_e32 v97, v97, v97
	v_max_f32_e32 v114, v114, v114
	v_max_f32_e32 v115, v115, v115
	v_lshl_add_u64 v[112:113], s[2:3], 0, v[112:113]
	v_max_f32_e32 v108, 0, v108
	v_max_f32_e32 v109, 0, v109
	v_max_f32_e32 v110, 0, v110
	v_max_f32_e32 v111, 0, v111
	v_max_f32_e32 v104, v104, v104
	v_max_f32_e32 v105, v105, v105
	v_max_f32_e32 v106, v106, v106
	v_max_f32_e32 v107, v107, v107
	v_max_f32_e32 v100, 0, v100
	v_max_f32_e32 v101, 0, v101
	v_max_f32_e32 v102, 0, v102
	v_max_f32_e32 v103, 0, v103
	v_max_f32_e32 v96, 0, v96
	v_max_f32_e32 v97, 0, v97
	v_max_f32_e32 v114, 0, v114
	v_max_f32_e32 v115, 0, v115
	v_lshl_add_u64 v[112:113], v[112:113], 0, v[142:143]
	v_pk_mul_f32 v[110:111], v[110:111], v[110:111]
	v_pk_mul_f32 v[108:109], v[108:109], v[108:109]
	v_max_f32_e32 v104, 0, v104
	v_max_f32_e32 v105, 0, v105
	v_max_f32_e32 v106, 0, v106
	v_max_f32_e32 v107, 0, v107
	v_pk_mul_f32 v[102:103], v[102:103], v[102:103]
	v_pk_mul_f32 v[100:101], v[100:101], v[100:101]
	v_pk_mul_f32 v[96:97], v[96:97], v[96:97]
	v_pk_mul_f32 v[114:115], v[114:115], v[114:115]
	v_pk_mul_f32 v[106:107], v[106:107], v[106:107]
	v_cvt_pk_bf16_f32 v119, v114, v115
	global_store_dwordx4 v[138:139], v[116:119], off offset:64 nt
	v_cvt_pk_bf16_f32 v108, v108, v109
	v_cvt_pk_bf16_f32 v109, v110, v111
	v_pk_mul_f32 v[104:105], v[104:105], v[104:105]
	v_max_f32_e32 v92, v92, v92
	v_cvt_pk_bf16_f32 v110, v104, v105
	v_cvt_pk_bf16_f32 v111, v106, v107
	global_store_dwordx4 v[112:113], v[108:111], off nt
	v_cvt_pk_bf16_f32 v100, v100, v101
	v_cvt_pk_bf16_f32 v101, v102, v103
	v_cvt_pk_bf16_f32 v102, v96, v97
	v_or_b32_e32 v96, 32, v140
	v_ashrrev_i32_e32 v97, 31, v96
	v_lshlrev_b64 v[96:97], 13, v[96:97]
	v_max_f32_e32 v93, v93, v93
	v_max_f32_e32 v94, v94, v94
	v_max_f32_e32 v95, v95, v95
	v_max_f32_e32 v84, v84, v84
	v_max_f32_e32 v85, v85, v85
	v_max_f32_e32 v86, v86, v86
	v_max_f32_e32 v87, v87, v87
	v_max_f32_e32 v80, v80, v80
	v_max_f32_e32 v81, v81, v81
	v_max_f32_e32 v98, v98, v98
	v_max_f32_e32 v99, v99, v99
	v_lshl_add_u64 v[96:97], s[2:3], 0, v[96:97]
	v_max_f32_e32 v92, 0, v92
	v_max_f32_e32 v93, 0, v93
	v_max_f32_e32 v94, 0, v94
	v_max_f32_e32 v95, 0, v95
	v_max_f32_e32 v88, v88, v88
	v_max_f32_e32 v89, v89, v89
	v_max_f32_e32 v90, v90, v90
	v_max_f32_e32 v91, v91, v91
	v_max_f32_e32 v84, 0, v84
	v_max_f32_e32 v85, 0, v85
	v_max_f32_e32 v86, 0, v86
	v_max_f32_e32 v87, 0, v87
	v_max_f32_e32 v80, 0, v80
	v_max_f32_e32 v81, 0, v81
	v_max_f32_e32 v98, 0, v98
	v_max_f32_e32 v99, 0, v99
	v_lshl_add_u64 v[96:97], v[96:97], 0, v[142:143]
	v_pk_mul_f32 v[94:95], v[94:95], v[94:95]
	v_pk_mul_f32 v[92:93], v[92:93], v[92:93]
	v_max_f32_e32 v88, 0, v88
	v_max_f32_e32 v89, 0, v89
	v_max_f32_e32 v90, 0, v90
	v_max_f32_e32 v91, 0, v91
	v_pk_mul_f32 v[86:87], v[86:87], v[86:87]
	v_pk_mul_f32 v[84:85], v[84:85], v[84:85]
	v_pk_mul_f32 v[80:81], v[80:81], v[80:81]
	v_pk_mul_f32 v[98:99], v[98:99], v[98:99]
	v_pk_mul_f32 v[90:91], v[90:91], v[90:91]
	v_cvt_pk_bf16_f32 v103, v98, v99
	global_store_dwordx4 v[112:113], v[100:103], off offset:64 nt
	v_cvt_pk_bf16_f32 v92, v92, v93
	v_cvt_pk_bf16_f32 v93, v94, v95
	v_pk_mul_f32 v[88:89], v[88:89], v[88:89]
	v_max_f32_e32 v76, v76, v76
	v_cvt_pk_bf16_f32 v94, v88, v89
	v_cvt_pk_bf16_f32 v95, v90, v91
	global_store_dwordx4 v[96:97], v[92:95], off nt
	v_cvt_pk_bf16_f32 v84, v84, v85
	v_cvt_pk_bf16_f32 v85, v86, v87
	v_cvt_pk_bf16_f32 v86, v80, v81
	v_or_b32_e32 v80, 48, v140
	v_ashrrev_i32_e32 v81, 31, v80
	v_lshlrev_b64 v[80:81], 13, v[80:81]
	v_max_f32_e32 v77, v77, v77
	v_max_f32_e32 v78, v78, v78
	v_max_f32_e32 v79, v79, v79
	v_max_f32_e32 v68, v68, v68
	v_max_f32_e32 v69, v69, v69
	v_max_f32_e32 v70, v70, v70
	v_max_f32_e32 v71, v71, v71
	v_max_f32_e32 v60, v60, v60
	v_max_f32_e32 v61, v61, v61
	v_max_f32_e32 v62, v62, v62
	v_max_f32_e32 v63, v63, v63
	v_max_f32_e32 v56, v56, v56
	v_max_f32_e32 v57, v57, v57
	v_max_f32_e32 v82, v82, v82
	v_max_f32_e32 v83, v83, v83
	v_lshl_add_u64 v[80:81], s[2:3], 0, v[80:81]
	v_max_f32_e32 v76, 0, v76
	v_max_f32_e32 v77, 0, v77
	v_max_f32_e32 v78, 0, v78
	v_max_f32_e32 v79, 0, v79
	v_max_f32_e32 v72, v72, v72
	v_max_f32_e32 v73, v73, v73
	v_max_f32_e32 v74, v74, v74
	v_max_f32_e32 v75, v75, v75
	v_max_f32_e32 v68, 0, v68
	v_max_f32_e32 v69, 0, v69
	v_max_f32_e32 v70, 0, v70
	v_max_f32_e32 v71, 0, v71
	v_max_f32_e32 v64, v64, v64
	v_max_f32_e32 v65, v65, v65
	v_max_f32_e32 v66, v66, v66
	v_max_f32_e32 v67, v67, v67
	v_max_f32_e32 v60, 0, v60
	v_max_f32_e32 v61, 0, v61
	v_max_f32_e32 v62, 0, v62
	v_max_f32_e32 v63, 0, v63
	v_max_f32_e32 v56, 0, v56
	v_max_f32_e32 v57, 0, v57
	v_max_f32_e32 v82, 0, v82
	v_max_f32_e32 v83, 0, v83
	v_lshl_add_u64 v[80:81], v[80:81], 0, v[142:143]
	v_pk_mul_f32 v[78:79], v[78:79], v[78:79]
	v_pk_mul_f32 v[76:77], v[76:77], v[76:77]
	v_max_f32_e32 v72, 0, v72
	v_max_f32_e32 v73, 0, v73
	v_max_f32_e32 v74, 0, v74
	v_max_f32_e32 v75, 0, v75
	v_pk_mul_f32 v[70:71], v[70:71], v[70:71]
	v_pk_mul_f32 v[68:69], v[68:69], v[68:69]
	v_max_f32_e32 v64, 0, v64
	v_max_f32_e32 v65, 0, v65
	v_max_f32_e32 v66, 0, v66
	v_max_f32_e32 v67, 0, v67
	v_pk_mul_f32 v[62:63], v[62:63], v[62:63]
	v_pk_mul_f32 v[60:61], v[60:61], v[60:61]
	v_pk_mul_f32 v[56:57], v[56:57], v[56:57]
	s_mov_b32 s11, 0x100000
	v_max_f32_e32 v52, v52, v52
	v_max_f32_e32 v53, v53, v53
	v_max_f32_e32 v54, v54, v54
	v_max_f32_e32 v55, v55, v55
	v_max_f32_e32 v44, v44, v44
	v_max_f32_e32 v45, v45, v45
	v_max_f32_e32 v46, v46, v46
	v_max_f32_e32 v47, v47, v47
	v_pk_mul_f32 v[82:83], v[82:83], v[82:83]
	v_pk_mul_f32 v[74:75], v[74:75], v[74:75]
	v_cvt_pk_bf16_f32 v87, v82, v83
	global_store_dwordx4 v[96:97], v[84:87], off offset:64 nt
	v_cvt_pk_bf16_f32 v76, v76, v77
	v_cvt_pk_bf16_f32 v77, v78, v79
	v_pk_mul_f32 v[72:73], v[72:73], v[72:73]
	v_pk_mul_f32 v[66:67], v[66:67], v[66:67]
	v_cvt_pk_bf16_f32 v78, v72, v73
	v_cvt_pk_bf16_f32 v79, v74, v75
	global_store_dwordx4 v[80:81], v[76:79], off nt
	v_cvt_pk_bf16_f32 v68, v68, v69
	v_cvt_pk_bf16_f32 v69, v70, v71
	v_pk_mul_f32 v[64:65], v[64:65], v[64:65]
	v_max_f32_e32 v58, v58, v58
	v_cvt_pk_bf16_f32 v70, v64, v65
	v_cvt_pk_bf16_f32 v71, v66, v67
	global_store_dwordx4 v[80:81], v[68:71], off offset:64 nt
	v_cvt_pk_bf16_f32 v60, v60, v61
	v_cvt_pk_bf16_f32 v61, v62, v63
	v_max_f32_e32 v59, v59, v59
	v_cvt_pk_bf16_f32 v62, v56, v57
	v_add_co_u32_e32 v56, vcc, s11, v138
	v_max_f32_e32 v52, 0, v52
	v_max_f32_e32 v53, 0, v53
	v_max_f32_e32 v54, 0, v54
	v_max_f32_e32 v55, 0, v55
	v_max_f32_e32 v44, 0, v44
	v_max_f32_e32 v45, 0, v45
	v_max_f32_e32 v46, 0, v46
	v_max_f32_e32 v47, 0, v47
	v_max_f32_e32 v58, 0, v58
	v_max_f32_e32 v59, 0, v59
	v_addc_co_u32_e32 v57, vcc, 0, v139, vcc
	v_pk_mul_f32 v[54:55], v[54:55], v[54:55]
	v_pk_mul_f32 v[52:53], v[52:53], v[52:53]
	v_pk_mul_f32 v[46:47], v[46:47], v[46:47]
	v_pk_mul_f32 v[44:45], v[44:45], v[44:45]
	v_pk_mul_f32 v[58:59], v[58:59], v[58:59]
	v_max_f32_e32 v40, v40, v40
	v_cvt_pk_bf16_f32 v63, v58, v59
	global_store_dwordx4 v[56:57], v[60:63], off nt
	v_cvt_pk_bf16_f32 v52, v52, v53
	v_cvt_pk_bf16_f32 v53, v54, v55
	v_cvt_pk_bf16_f32 v54, v44, v45
	v_cvt_pk_bf16_f32 v55, v46, v47
	v_max_f32_e32 v44, v48, v48
	v_max_f32_e32 v45, v49, v49
	v_max_f32_e32 v46, v50, v50
	v_max_f32_e32 v47, v51, v51
	v_max_f32_e32 v41, v41, v41
	s_mov_b64 s[16:17], 0x100000
	v_max_f32_e32 v44, 0, v44
	v_max_f32_e32 v45, 0, v45
	v_max_f32_e32 v46, 0, v46
	v_max_f32_e32 v47, 0, v47
	v_max_f32_e32 v40, 0, v40
	v_max_f32_e32 v41, 0, v41
	v_lshl_add_u64 v[64:65], v[138:139], 0, s[16:17]
	v_pk_mul_f32 v[46:47], v[46:47], v[46:47]
	v_pk_mul_f32 v[44:45], v[44:45], v[44:45]
	v_pk_mul_f32 v[40:41], v[40:41], v[40:41]
	s_mov_b32 s11, 0x120000
	v_max_f32_e32 v36, v36, v36
	v_max_f32_e32 v37, v37, v37
	v_max_f32_e32 v38, v38, v38
	v_max_f32_e32 v39, v39, v39
	v_max_f32_e32 v28, v28, v28
	v_max_f32_e32 v29, v29, v29
	v_max_f32_e32 v30, v30, v30
	v_max_f32_e32 v31, v31, v31
	global_store_dwordx4 v[64:65], v[52:55], off offset:64 nt
	v_cvt_pk_bf16_f32 v44, v44, v45
	v_cvt_pk_bf16_f32 v45, v46, v47
	v_max_f32_e32 v42, v42, v42
	v_max_f32_e32 v43, v43, v43
	v_cvt_pk_bf16_f32 v46, v40, v41
	v_add_co_u32_e32 v40, vcc, s11, v138
	v_max_f32_e32 v36, 0, v36
	v_max_f32_e32 v37, 0, v37
	v_max_f32_e32 v38, 0, v38
	v_max_f32_e32 v39, 0, v39
	v_max_f32_e32 v28, 0, v28
	v_max_f32_e32 v29, 0, v29
	v_max_f32_e32 v30, 0, v30
	v_max_f32_e32 v31, 0, v31
	v_max_f32_e32 v42, 0, v42
	v_max_f32_e32 v43, 0, v43
	v_addc_co_u32_e32 v41, vcc, 0, v139, vcc
	v_pk_mul_f32 v[38:39], v[38:39], v[38:39]
	v_pk_mul_f32 v[36:37], v[36:37], v[36:37]
	v_pk_mul_f32 v[30:31], v[30:31], v[30:31]
	v_pk_mul_f32 v[28:29], v[28:29], v[28:29]
	v_pk_mul_f32 v[42:43], v[42:43], v[42:43]
	v_max_f32_e32 v24, v24, v24
	v_cvt_pk_bf16_f32 v47, v42, v43
	global_store_dwordx4 v[40:41], v[44:47], off nt
	v_cvt_pk_bf16_f32 v36, v36, v37
	v_cvt_pk_bf16_f32 v37, v38, v39
	v_cvt_pk_bf16_f32 v38, v28, v29
	v_cvt_pk_bf16_f32 v39, v30, v31
	v_max_f32_e32 v28, v32, v32
	v_max_f32_e32 v29, v33, v33
	v_max_f32_e32 v30, v34, v34
	v_max_f32_e32 v31, v35, v35
	v_max_f32_e32 v25, v25, v25
	s_mov_b64 s[16:17], 0x120000
	v_max_f32_e32 v28, 0, v28
	v_max_f32_e32 v29, 0, v29
	v_max_f32_e32 v30, 0, v30
	v_max_f32_e32 v31, 0, v31
	v_max_f32_e32 v24, 0, v24
	v_max_f32_e32 v25, 0, v25
	v_lshl_add_u64 v[52:53], v[138:139], 0, s[16:17]
	v_pk_mul_f32 v[30:31], v[30:31], v[30:31]
	v_pk_mul_f32 v[28:29], v[28:29], v[28:29]
	v_pk_mul_f32 v[24:25], v[24:25], v[24:25]
	s_mov_b32 s11, 0x140000
	v_max_f32_e32 v20, v20, v20
	v_max_f32_e32 v21, v21, v21
	v_max_f32_e32 v22, v22, v22
	v_max_f32_e32 v23, v23, v23
	v_max_f32_e32 v12, v12, v12
	v_max_f32_e32 v13, v13, v13
	v_max_f32_e32 v14, v14, v14
	v_max_f32_e32 v15, v15, v15
	global_store_dwordx4 v[52:53], v[36:39], off offset:64 nt
	v_cvt_pk_bf16_f32 v28, v28, v29
	v_cvt_pk_bf16_f32 v29, v30, v31
	v_max_f32_e32 v26, v26, v26
	v_max_f32_e32 v27, v27, v27
	v_cvt_pk_bf16_f32 v30, v24, v25
	v_add_co_u32_e32 v24, vcc, s11, v138
	v_max_f32_e32 v20, 0, v20
	v_max_f32_e32 v21, 0, v21
	v_max_f32_e32 v22, 0, v22
	v_max_f32_e32 v23, 0, v23
	v_max_f32_e32 v12, 0, v12
	v_max_f32_e32 v13, 0, v13
	v_max_f32_e32 v14, 0, v14
	v_max_f32_e32 v15, 0, v15
	v_max_f32_e32 v26, 0, v26
	v_max_f32_e32 v27, 0, v27
	v_addc_co_u32_e32 v25, vcc, 0, v139, vcc
	v_pk_mul_f32 v[22:23], v[22:23], v[22:23]
	v_pk_mul_f32 v[20:21], v[20:21], v[20:21]
	v_pk_mul_f32 v[14:15], v[14:15], v[14:15]
	v_pk_mul_f32 v[12:13], v[12:13], v[12:13]
	v_pk_mul_f32 v[26:27], v[26:27], v[26:27]
	v_max_f32_e32 v8, v8, v8
	v_cvt_pk_bf16_f32 v31, v26, v27
	global_store_dwordx4 v[24:25], v[28:31], off nt
	v_cvt_pk_bf16_f32 v20, v20, v21
	v_cvt_pk_bf16_f32 v21, v22, v23
	v_cvt_pk_bf16_f32 v22, v12, v13
	v_cvt_pk_bf16_f32 v23, v14, v15
	v_max_f32_e32 v12, v16, v16
	v_max_f32_e32 v13, v17, v17
	v_max_f32_e32 v14, v18, v18
	v_max_f32_e32 v15, v19, v19
	v_max_f32_e32 v9, v9, v9
	s_mov_b64 s[16:17], 0x140000
	v_max_f32_e32 v12, 0, v12
	v_max_f32_e32 v13, 0, v13
	v_max_f32_e32 v14, 0, v14
	v_max_f32_e32 v15, 0, v15
	v_max_f32_e32 v8, 0, v8
	v_max_f32_e32 v9, 0, v9
	v_lshl_add_u64 v[36:37], v[138:139], 0, s[16:17]
	v_pk_mul_f32 v[14:15], v[14:15], v[14:15]
	v_pk_mul_f32 v[12:13], v[12:13], v[12:13]
	v_pk_mul_f32 v[8:9], v[8:9], v[8:9]
	s_mov_b32 s11, 0x160000
	global_store_dwordx4 v[36:37], v[20:23], off offset:64 nt
	v_cvt_pk_bf16_f32 v12, v12, v13
	v_cvt_pk_bf16_f32 v13, v14, v15
	v_cvt_pk_bf16_f32 v14, v8, v9
	v_add_co_u32_e32 v8, vcc, s11, v138
	v_max_f32_e32 v4, v4, v4
	v_max_f32_e32 v5, v5, v5
	v_max_f32_e32 v6, v6, v6
	v_max_f32_e32 v7, v7, v7
	s_mov_b64 s[16:17], 0x160000
	v_max_f32_e32 v10, v10, v10
	v_max_f32_e32 v11, v11, v11
	v_addc_co_u32_e32 v9, vcc, 0, v139, vcc
	v_max_f32_e32 v4, 0, v4
	v_max_f32_e32 v5, 0, v5
	v_max_f32_e32 v6, 0, v6
	v_max_f32_e32 v7, 0, v7
	v_max_f32_e32 v0, v0, v0
	v_max_f32_e32 v1, v1, v1
	v_max_f32_e32 v2, v2, v2
	v_max_f32_e32 v3, v3, v3
	v_lshl_add_u64 v[20:21], v[138:139], 0, s[16:17]
	v_max_f32_e32 v10, 0, v10
	v_max_f32_e32 v11, 0, v11
	v_pk_mul_f32 v[6:7], v[6:7], v[6:7]
	v_pk_mul_f32 v[4:5], v[4:5], v[4:5]
	v_max_f32_e32 v0, 0, v0
	v_max_f32_e32 v1, 0, v1
	v_max_f32_e32 v2, 0, v2
	v_max_f32_e32 v3, 0, v3
	s_andn2_b64 vcc, exec, s[38:39]
	s_mov_b64 s[16:17], -1
	s_mov_b64 s[80:81], 0xc00000
	s_mov_b64 s[84:85], 0xc00800
	v_pk_mul_f32 v[10:11], v[10:11], v[10:11]
	v_pk_mul_f32 v[2:3], v[2:3], v[2:3]
	v_cvt_pk_bf16_f32 v15, v10, v11
	global_store_dwordx4 v[8:9], v[12:15], off nt
	v_cvt_pk_bf16_f32 v4, v4, v5
	v_cvt_pk_bf16_f32 v5, v6, v7
	v_pk_mul_f32 v[0:1], v[0:1], v[0:1]
	s_nop 0
	v_cvt_pk_bf16_f32 v6, v0, v1
	v_cvt_pk_bf16_f32 v7, v2, v3
	global_store_dwordx4 v[20:21], v[4:7], off offset:64 nt
	s_cbranch_vccnz .LBB0_231
	s_andn2_b64 vcc, exec, s[0:1]
	s_cbranch_vccnz .LBB0_230
	s_barrier
	s_branch .LBB0_230
